# grid barrier: non-leader workgroups poll the top generation word directly (one device-scope hop less per barrier)
# speedup vs baseline: 1.0085x; 1.0074x over previous
.LBB0_38:
	s_or_b64 exec, exec, s[20:21]
	v_cvt_f32_u32_e32 v4, v2
	s_waitcnt vmcnt(0)
	v_readfirstlane_b32 s2, v3
	v_sub_u32_e32 v3, 0, v2
	v_rcp_iflag_f32_e32 v4, v4
	v_add_u32_e32 v5, s2, v1
	v_mul_f32_e32 v4, 0x4f7ffffe, v4
	v_cvt_u32_f32_e32 v4, v4
	v_mul_lo_u32 v1, v3, v4
	v_mul_hi_u32 v1, v4, v1
	v_add_u32_e32 v1, v4, v1
	v_mul_hi_u32 v1, v5, v1
	v_mul_lo_u32 v3, v1, v2
	v_sub_u32_e32 v3, v5, v3
	v_add_u32_e32 v4, 1, v1
	v_sub_u32_e32 v6, v3, v2
	v_cmp_ge_u32_e32 vcc, v3, v2
	s_nop 1
	v_cndmask_b32_e32 v1, v1, v4, vcc
	v_cndmask_b32_e32 v3, v3, v6, vcc
	v_add_u32_e32 v4, 1, v1
	v_cmp_ge_u32_e32 vcc, v3, v2
	v_add_u32_e32 v3, 1, v5
	s_nop 0
	v_cndmask_b32_e32 v1, v1, v4, vcc
	v_mul_lo_u32 v4, v2, v1
	v_add_u32_e32 v2, v4, v2
	v_cmp_ne_u32_e32 vcc, v3, v2
	s_and_saveexec_b64 s[20:21], vcc
	s_xor_b64 s[20:21], exec, s[20:21]
	s_cbranch_execz .LBB0_52
	v_readlane_b32 s22, v215, 18
	v_readlane_b32 s23, v215, 19
	s_waitcnt lgkmcnt(0)
	s_nop 3
	global_load_dword v0, v65, s[22:23] sc1
	s_waitcnt vmcnt(0)
	v_cmp_eq_u32_e32 vcc, v0, v1
	s_and_saveexec_b64 s[28:29], vcc
	s_cbranch_execz .LBB0_51
	s_mov_b32 s2, 1
	s_mov_b64 s[34:35], 0
	s_branch .LBB0_42

.LBB0_44:
	v_readlane_b32 s22, v215, 18
	v_readlane_b32 s23, v215, 19
	s_add_i32 s2, s2, 1
	s_mov_b64 s[40:41], -1
	s_nop 2
	global_load_dword v0, v65, s[22:23] sc1
	s_waitcnt vmcnt(0)
	v_cmp_ne_u32_e32 vcc, v0, v1
	s_orn2_b64 s[38:39], vcc, exec
	s_branch .LBB0_41
